# v105 + hgrn_post wave sums via DPP row reduction + readlanes (all four items) instead of 6-stage ds_bpermute chains
# baseline (speedup 1.0000x reference)
.LBB0_485:
	s_ashr_i32 s0, s4, 2
	s_mul_hi_i32 s1, s0, 0x3080
	s_mulk_i32 s0, 0x3080
	s_add_u32 s5, s34, s0
	s_addc_u32 s1, s35, s1
	s_and_b32 s0, s10, 0x180
	s_lshl_b32 s6, s0, 1
	s_add_u32 s6, s5, s6
	s_addc_u32 s7, s1, 0
	v_lshl_add_u64 v[0:1], s[6:7], 0, v[30:31]
	s_movk_i32 s14, 0x1000
	v_add_co_u32_e32 v4, vcc, s14, v0
	s_movk_i32 s15, 0x2000
	s_nop 0
	v_addc_co_u32_e32 v5, vcc, 0, v1, vcc
	global_load_dword v23, v[4:5], off offset:3584
	v_add_co_u32_e32 v0, vcc, s15, v0
	s_add_i32 s1, s12, s4
	s_nop 0
	v_addc_co_u32_e32 v1, vcc, 0, v1, vcc
	global_load_dword v32, v[0:1], off offset:512
	s_cmp_lt_i32 s1, 0x10000
	s_cselect_b32 s5, s1, s4
	s_ashr_i32 s6, s5, 2
	s_mul_hi_i32 s7, s6, 0x3080
	s_mulk_i32 s6, 0x3080
	s_add_u32 s6, s34, s6
	s_addc_u32 s7, s35, s7
	s_lshl_b32 s5, s5, 8
	s_and_b32 s5, s5, 0x300
	s_add_u32 s6, s6, s5
	s_addc_u32 s7, s7, 0
	s_add_i32 s5, s12, s1
	s_cmp_lt_i32 s5, 0x10000
	s_cselect_b64 s[8:9], -1, 0
	v_lshl_add_u64 v[8:9], s[6:7], 0, v[30:31]
	s_and_b64 s[6:7], s[8:9], exec
	s_cselect_b32 s6, s5, s4
	s_ashr_i32 s7, s6, 2
	s_mul_hi_i32 s11, s7, 0x3080
	s_mulk_i32 s7, 0x3080
	s_add_u32 s7, s34, s7
	s_addc_u32 s11, s35, s11
	s_lshl_b32 s6, s6, 8
	s_and_b32 s6, s6, 0x300
	s_add_u32 s6, s7, s6
	s_addc_u32 s7, s11, 0
	s_add_i32 s11, s12, s5
	s_cmp_lt_i32 s11, 0x10000
	s_waitcnt lgkmcnt(0)
	v_lshl_add_u64 v[6:7], s[6:7], 0, v[30:31]
	s_cselect_b64 s[6:7], -1, 0
	s_and_b64 s[12:13], s[6:7], exec
	s_cselect_b32 s4, s11, s4
	v_add_co_u32_e32 v2, vcc, s14, v8
	s_ashr_i32 s5, s4, 2
	s_nop 0
	v_addc_co_u32_e32 v3, vcc, 0, v9, vcc
	s_mul_hi_i32 s12, s5, 0x3080
	s_mulk_i32 s5, 0x3080
	v_add_co_u32_e32 v10, vcc, s15, v8
	s_add_u32 s5, s34, s5
	s_nop 0
	v_addc_co_u32_e32 v11, vcc, 0, v9, vcc
	s_addc_u32 s12, s35, s12
	s_lshl_b32 s4, s4, 8
	v_add_co_u32_e32 v20, vcc, s14, v6
	s_and_b32 s4, s4, 0x300
	s_nop 0
	v_addc_co_u32_e32 v21, vcc, 0, v7, vcc
	s_add_u32 s4, s5, s4
	v_add_co_u32_e32 v24, vcc, s15, v6
	s_addc_u32 s5, s12, 0
	s_nop 0
	v_addc_co_u32_e32 v25, vcc, 0, v7, vcc
	v_lshl_add_u64 v[0:1], s[4:5], 0, v[30:31]
	v_add_co_u32_e32 v26, vcc, s14, v0
	s_cmp_gt_i32 s1, 0xffff
	s_nop 0
	v_addc_co_u32_e32 v27, vcc, 0, v1, vcc
	v_add_co_u32_e32 v28, vcc, s15, v0
	s_nop 1
	v_addc_co_u32_e32 v29, vcc, 0, v1, vcc
	global_load_dword v33, v[2:3], off offset:3584
	s_nop 0
	global_load_dword v10, v[10:11], off offset:512
	s_nop 0
	global_load_dword v22, v[20:21], off offset:3584
	s_nop 0
	global_load_dword v21, v[24:25], off offset:512
	global_load_dword v20, v[26:27], off offset:3584
	global_load_dword v19, v[28:29], off offset:512
	v_or_b32_e32 v11, s0, v18
	s_mov_b32 s0, 0xf800000
	s_waitcnt vmcnt(0)
	v_lshlrev_b32_e32 v25, 16, v23
	v_and_b32_e32 v27, 0xffff0000, v23
	v_mov_b32_e32 v2, v25
	v_mov_b32_e32 v3, v27
	v_pk_mul_f32 v[2:3], v[2:3], v[2:3]
	v_and_b32_e32 v26, 0xffff0000, v32
	v_add_f32_e32 v2, v2, v3
	v_mov_b32_e32 v200, v2
	s_nop 1
	v_add_f32_dpp v200, v200, v200 quad_perm:[1,0,3,2] row_mask:0xf bank_mask:0xf bound_ctrl:1
	s_nop 1
	v_add_f32_dpp v200, v200, v200 quad_perm:[2,3,0,1] row_mask:0xf bank_mask:0xf bound_ctrl:1
	s_nop 1
	v_add_f32_dpp v200, v200, v200 row_half_mirror row_mask:0xf bank_mask:0xf bound_ctrl:1
	s_nop 1
	v_add_f32_dpp v200, v200, v200 row_mirror row_mask:0xf bank_mask:0xf bound_ctrl:1
	s_nop 0
	v_readlane_b32 s16, v200, 0
	v_readlane_b32 s17, v200, 16
	s_nop 0
	v_mov_b32_e32 v202, s16
	v_add_f32_e32 v202, s17, v202
	v_readlane_b32 s16, v200, 32
	v_readlane_b32 s17, v200, 48
	s_nop 0
	v_add_f32_e32 v202, s16, v202
	v_add_f32_e32 v200, s17, v202
	v_mul_f32_e32 v29, 0xbfb8aa3b, v26
	v_exp_f32_e32 v29, v29
	v_lshlrev_b32_e32 v24, 16, v32
	s_waitcnt lgkmcnt(0)
	v_lshlrev_b32_e32 v2, 2, v11
	global_load_dwordx2 v[2:3], v2, s[2:3]
	v_add_f32_e32 v29, 1.0, v29
	s_waitcnt lgkmcnt(0)
	v_mul_f32_e32 v28, 0xbfb8aa3b, v24
	v_exp_f32_e32 v28, v28
	s_waitcnt lgkmcnt(0)
	v_add_f32_e32 v35, 1.0, v28
	s_waitcnt lgkmcnt(0)
	s_waitcnt lgkmcnt(0)
	v_rcp_f32_e32 v28, v29
	s_waitcnt lgkmcnt(0)
	v_mov_b32_e32 v11, v200
	v_fmamk_f32 v11, v11, 0x3c000000, v188
	v_mul_f32_e32 v23, 0x4f800000, v11
	v_cmp_gt_f32_e64 s[0:1], s0, v11
	s_nop 1
	v_cndmask_b32_e64 v11, v11, v23, s[0:1]
	v_sqrt_f32_e32 v23, v11
	s_nop 0
	v_add_u32_e32 v32, -1, v23
	v_fma_f32 v37, -v32, v23, v11
	v_cmp_ge_f32_e64 s[4:5], 0, v37
	v_add_u32_e32 v37, 1, v23
	s_nop 0
	v_cndmask_b32_e64 v32, v23, v32, s[4:5]
	v_fma_f32 v23, -v37, v23, v11
	v_cmp_lt_f32_e64 s[4:5], 0, v23
	s_nop 1
	v_cndmask_b32_e64 v23, v32, v37, s[4:5]
	v_mul_f32_e32 v32, 0x37800000, v23
	v_cndmask_b32_e64 v23, v23, v32, s[0:1]
	v_cmp_class_f32_e64 s[0:1], v11, v189
	s_nop 1
	v_cndmask_b32_e64 v32, v23, v11, s[0:1]
	v_and_b32_e32 v23, 0xffff0000, v33
	v_lshlrev_b32_e32 v11, 16, v33
	v_mul_f32_e32 v34, v23, v23
	v_fmac_f32_e32 v34, v11, v11
	v_mov_b32_e32 v204, v34
	s_nop 1
	v_add_f32_dpp v204, v204, v204 quad_perm:[1,0,3,2] row_mask:0xf bank_mask:0xf bound_ctrl:1
	s_nop 1
	v_add_f32_dpp v204, v204, v204 quad_perm:[2,3,0,1] row_mask:0xf bank_mask:0xf bound_ctrl:1
	s_nop 1
	v_add_f32_dpp v204, v204, v204 row_half_mirror row_mask:0xf bank_mask:0xf bound_ctrl:1
	s_nop 1
	v_add_f32_dpp v204, v204, v204 row_mirror row_mask:0xf bank_mask:0xf bound_ctrl:1
	s_nop 0
	v_readlane_b32 s16, v204, 0
	v_readlane_b32 s17, v204, 16
	s_nop 0
	v_mov_b32_e32 v206, s16
	v_add_f32_e32 v206, s17, v206
	v_readlane_b32 s16, v204, 32
	v_readlane_b32 s17, v204, 48
	s_nop 0
	v_add_f32_e32 v206, s16, v206
	v_add_f32_e32 v204, s17, v206
	v_rcp_f32_e32 v33, v32
	s_waitcnt lgkmcnt(0)
	s_waitcnt lgkmcnt(0)
	s_waitcnt lgkmcnt(0)
	v_rcp_f32_e32 v32, v35
	v_mov_b32_e32 v29, v33
	v_pk_mul_f32 v[26:27], v[28:29], v[26:27]
	s_waitcnt lgkmcnt(0)
	s_waitcnt vmcnt(0)
	v_mul_f32_e32 v27, v3, v27
	v_mul_f32_e32 v28, v26, v27
	v_pk_mul_f32 v[26:27], v[32:33], v[24:25]
	s_waitcnt lgkmcnt(0)
	v_mul_f32_e32 v27, v2, v27
	v_mul_f32_e32 v26, v26, v27
	v_cvt_pk_bf16_f32 v26, v26, v28
	global_store_dword v[4:5], v26, off offset:3584
	s_cbranch_scc1 .LBB0_487
	v_and_b32_e32 v26, 0xffff0000, v10
	v_mul_f32_e32 v4, 0xbfb8aa3b, v26
	v_exp_f32_e32 v27, v4
	s_mov_b64 s[0:1], 0x1e00
	v_lshl_add_u64 v[4:5], v[8:9], 0, s[0:1]
	s_waitcnt lgkmcnt(0)
	v_mov_b32_e32 v24, v204
	v_add_f32_e32 v8, 1.0, v27
	v_fmamk_f32 v24, v24, 0x3c000000, v188
	s_mov_b32 s0, 0xf800000
	v_mul_f32_e32 v25, 0x4f800000, v24
	v_cmp_gt_f32_e32 vcc, s0, v24
	v_lshlrev_b32_e32 v10, 16, v10
	v_mul_f32_e32 v27, 0xbfb8aa3b, v10
	v_cndmask_b32_e32 v24, v24, v25, vcc
	v_sqrt_f32_e32 v25, v24
	v_rcp_f32_e32 v8, v8
	v_exp_f32_e32 v27, v27
	v_mul_f32_e32 v26, v8, v26
	v_add_u32_e32 v28, -1, v25
	v_fma_f32 v29, -v28, v25, v24
	v_cmp_ge_f32_e64 s[0:1], 0, v29
	v_add_u32_e32 v29, 1, v25
	v_add_f32_e32 v27, 1.0, v27
	v_cndmask_b32_e64 v28, v25, v28, s[0:1]
	v_fma_f32 v25, -v29, v25, v24
	v_cmp_lt_f32_e64 s[0:1], 0, v25
	s_nop 1
	v_cndmask_b32_e64 v25, v28, v29, s[0:1]
	v_mul_f32_e32 v28, 0x37800000, v25
	v_cndmask_b32_e32 v25, v25, v28, vcc
	v_cmp_class_f32_e32 vcc, v24, v189
	s_nop 1
	v_cndmask_b32_e32 v24, v25, v24, vcc
	s_nop 0
	v_rcp_f32_e32 v9, v24
	s_nop 0
	v_mul_f32_e32 v23, v9, v23
	v_rcp_f32_e32 v8, v27
	s_nop 0
	v_pk_mul_f32 v[8:9], v[8:9], v[10:11]
	v_mul_f32_e32 v23, v23, v3
	v_mul_f32_e32 v9, v9, v2
	v_mul_f32_e32 v8, v8, v9
	v_mul_f32_e32 v23, v26, v23
	v_cvt_pk_bf16_f32 v8, v8, v23
	global_store_dword v[4:5], v8, off
.LBB0_487:
	v_and_b32_e32 v8, 0xffff0000, v22
	v_lshlrev_b32_e32 v5, 16, v22
	v_mul_f32_e32 v4, v8, v8
	v_fmac_f32_e32 v4, v5, v5
	s_nop 1
	v_add_f32_dpp v4, v4, v4 quad_perm:[1,0,3,2] row_mask:0xf bank_mask:0xf bound_ctrl:1
	s_nop 1
	v_add_f32_dpp v4, v4, v4 quad_perm:[2,3,0,1] row_mask:0xf bank_mask:0xf bound_ctrl:1
	s_nop 1
	v_add_f32_dpp v4, v4, v4 row_half_mirror row_mask:0xf bank_mask:0xf bound_ctrl:1
	s_nop 1
	v_add_f32_dpp v4, v4, v4 row_mirror row_mask:0xf bank_mask:0xf bound_ctrl:1
	s_nop 0
	v_readlane_b32 s0, v4, 0
	v_readlane_b32 s1, v4, 16
	s_nop 0
	v_mov_b32_e32 v9, s0
	v_add_f32_e32 v9, s1, v9
	v_readlane_b32 s0, v4, 32
	v_readlane_b32 s1, v4, 48
	s_nop 0
	v_add_f32_e32 v9, s0, v9
	v_add_f32_e32 v4, s1, v9
	v_mov_b32_e32 v9, 0
	s_andn2_b64 vcc, exec, s[8:9]
	s_waitcnt lgkmcnt(0)
	s_waitcnt lgkmcnt(0)
	s_waitcnt lgkmcnt(0)
	s_waitcnt lgkmcnt(0)
	s_waitcnt lgkmcnt(0)
	s_cbranch_vccnz .LBB0_489
	v_and_b32_e32 v10, 0xffff0000, v21
	v_mul_f32_e32 v11, 0xbfb8aa3b, v10
	v_exp_f32_e32 v11, v11
	s_mov_b64 s[0:1], 0x1e00
	v_lshl_add_u64 v[6:7], v[6:7], 0, s[0:1]
	s_waitcnt lgkmcnt(0)
	v_add_f32_e32 v4, v4, v9
	v_add_f32_e32 v11, 1.0, v11
	v_fmamk_f32 v4, v4, 0x3c000000, v188
	s_mov_b32 s0, 0xf800000
	v_mul_f32_e32 v22, 0x4f800000, v4
	v_cmp_gt_f32_e32 vcc, s0, v4
	v_rcp_f32_e32 v9, v11
	s_nop 0
	v_mul_f32_e32 v9, v9, v10
	v_cndmask_b32_e32 v22, v4, v22, vcc
	v_sqrt_f32_e32 v23, v22
	v_lshlrev_b32_e32 v4, 16, v21
	v_mul_f32_e32 v21, 0xbfb8aa3b, v4
	v_exp_f32_e32 v21, v21
	v_add_u32_e32 v24, -1, v23
	v_fma_f32 v25, -v24, v23, v22
	v_cmp_ge_f32_e64 s[0:1], 0, v25
	v_add_u32_e32 v25, 1, v23
	v_add_f32_e32 v21, 1.0, v21
	v_cndmask_b32_e64 v24, v23, v24, s[0:1]
	v_fma_f32 v23, -v25, v23, v22
	v_cmp_lt_f32_e64 s[0:1], 0, v23
	s_nop 1
	v_cndmask_b32_e64 v23, v24, v25, s[0:1]
	v_mul_f32_e32 v24, 0x37800000, v23
	v_cndmask_b32_e32 v23, v23, v24, vcc
	v_cmp_class_f32_e32 vcc, v22, v189
	s_nop 1
	v_cndmask_b32_e32 v22, v23, v22, vcc
	s_nop 0
	v_div_scale_f32 v23, s[0:1], v21, v21, 1.0
	v_rcp_f32_e32 v25, v23
	v_rcp_f32_e32 v11, v22
	s_nop 0
	v_mul_f32_e32 v8, v11, v8
	v_fma_f32 v10, -v23, v25, 1.0
	v_fmac_f32_e32 v25, v10, v25
	v_div_scale_f32 v10, vcc, 1.0, v21, 1.0
	v_mul_f32_e32 v22, v10, v25
	v_fma_f32 v24, -v23, v22, v10
	v_fmac_f32_e32 v22, v24, v25
	v_fma_f32 v10, -v23, v22, v10
	v_div_fmas_f32 v10, v10, v25, v22
	v_div_fixup_f32 v10, v10, v21, 1.0
	v_pk_mul_f32 v[4:5], v[10:11], v[4:5]
	v_mul_f32_e32 v8, v8, v3
	v_mul_f32_e32 v5, v5, v2
	v_mul_f32_e32 v4, v4, v5
	v_mul_f32_e32 v8, v9, v8
	v_cvt_pk_bf16_f32 v4, v4, v8
	global_store_dword v[6:7], v4, off
.LBB0_489:
	v_and_b32_e32 v6, 0xffff0000, v20
	v_lshlrev_b32_e32 v5, 16, v20
	v_mul_f32_e32 v4, v6, v6
	v_fmac_f32_e32 v4, v5, v5
	s_nop 1
	v_add_f32_dpp v4, v4, v4 quad_perm:[1,0,3,2] row_mask:0xf bank_mask:0xf bound_ctrl:1
	s_nop 1
	v_add_f32_dpp v4, v4, v4 quad_perm:[2,3,0,1] row_mask:0xf bank_mask:0xf bound_ctrl:1
	s_nop 1
	v_add_f32_dpp v4, v4, v4 row_half_mirror row_mask:0xf bank_mask:0xf bound_ctrl:1
	s_nop 1
	v_add_f32_dpp v4, v4, v4 row_mirror row_mask:0xf bank_mask:0xf bound_ctrl:1
	s_nop 0
	v_readlane_b32 s0, v4, 0
	v_readlane_b32 s1, v4, 16
	s_nop 0
	v_mov_b32_e32 v7, s0
	v_add_f32_e32 v7, s1, v7
	v_readlane_b32 s0, v4, 32
	v_readlane_b32 s1, v4, 48
	s_nop 0
	v_add_f32_e32 v7, s0, v7
	v_add_f32_e32 v4, s1, v7
	v_mov_b32_e32 v7, 0
	s_andn2_b64 vcc, exec, s[6:7]
	s_waitcnt lgkmcnt(0)
	s_waitcnt lgkmcnt(0)
	s_waitcnt lgkmcnt(0)
	s_waitcnt lgkmcnt(0)
	s_waitcnt lgkmcnt(0)
	s_cbranch_vccnz .LBB0_484
	v_and_b32_e32 v8, 0xffff0000, v19
	v_mul_f32_e32 v9, 0xbfb8aa3b, v8
	v_exp_f32_e32 v9, v9
	s_mov_b64 s[0:1], 0x1e00
	v_lshl_add_u64 v[0:1], v[0:1], 0, s[0:1]
	s_waitcnt lgkmcnt(0)
	v_add_f32_e32 v4, v4, v7
	v_add_f32_e32 v9, 1.0, v9
	v_fmamk_f32 v4, v4, 0x3c000000, v188
	s_mov_b32 s0, 0xf800000
	v_mul_f32_e32 v10, 0x4f800000, v4
	v_cmp_gt_f32_e32 vcc, s0, v4
	v_rcp_f32_e32 v7, v9
	s_nop 0
	v_mul_f32_e32 v7, v7, v8
	v_cndmask_b32_e32 v10, v4, v10, vcc
	v_sqrt_f32_e32 v11, v10
	v_lshlrev_b32_e32 v4, 16, v19
	v_mul_f32_e32 v19, 0xbfb8aa3b, v4
	v_exp_f32_e32 v19, v19
	v_add_u32_e32 v20, -1, v11
	v_fma_f32 v21, -v20, v11, v10
	v_cmp_ge_f32_e64 s[0:1], 0, v21
	v_add_u32_e32 v21, 1, v11
	v_add_f32_e32 v19, 1.0, v19
	v_cndmask_b32_e64 v20, v11, v20, s[0:1]
	v_fma_f32 v11, -v21, v11, v10
	v_cmp_lt_f32_e64 s[0:1], 0, v11
	s_nop 1
	v_cndmask_b32_e64 v11, v20, v21, s[0:1]
	v_mul_f32_e32 v20, 0x37800000, v11
	v_cndmask_b32_e32 v11, v11, v20, vcc
	v_cmp_class_f32_e32 vcc, v10, v189
	s_nop 1
	v_cndmask_b32_e32 v10, v11, v10, vcc
	s_nop 0
	v_div_scale_f32 v11, s[0:1], v19, v19, 1.0
	v_rcp_f32_e32 v21, v11
	v_rcp_f32_e32 v9, v10
	s_nop 0
	v_mul_f32_e32 v6, v9, v6
	v_fma_f32 v8, -v11, v21, 1.0
	v_fmac_f32_e32 v21, v8, v21
	v_div_scale_f32 v8, vcc, 1.0, v19, 1.0
	v_mul_f32_e32 v10, v8, v21
	v_fma_f32 v20, -v11, v10, v8
	v_fmac_f32_e32 v10, v20, v21
	v_fma_f32 v8, -v11, v10, v8
	v_div_fmas_f32 v8, v8, v21, v10
	v_div_fixup_f32 v8, v8, v19, 1.0
	v_pk_mul_f32 v[4:5], v[8:9], v[4:5]
	v_mul_f32_e32 v3, v6, v3
	v_mul_f32_e32 v2, v5, v2
	v_mul_f32_e32 v2, v4, v2
	v_mul_f32_e32 v3, v7, v3
	v_cvt_pk_bf16_f32 v2, v2, v3
	global_store_dword v[0:1], v2, off
	s_branch .LBB0_484
